# sample-row GEMM items re-dealt (layer-loop phases): the workgroups that share a weight column slice now sit on one XCD (item = (wg&7)*32 + wg/8), so each slice is fetched into one L2 instead of 4-8
# speedup vs baseline: 1.0115x; 1.0110x over previous
.LBB0_394:
	s_add_u32 s4, s54, 0x20800
	v_writelane_b32 v253, s4, 10
	s_addc_u32 s4, s55, 0
	s_add_u32 s70, s54, 0x41000
	s_addc_u32 s71, s55, 0
	v_writelane_b32 v253, s4, 11
	s_add_u32 s4, s54, 0x61800
	v_writelane_b32 v253, s4, 12
	s_addc_u32 s4, s55, 0
	v_writelane_b32 v253, s4, 13
	s_add_u32 s4, s54, 0x82000
	s_addc_u32 s5, s55, 0
	s_add_u32 s74, s54, 0xc4000
	v_writelane_b32 v253, s4, 14
	s_addc_u32 s75, s55, 0
	s_load_dwordx2 s[6:7], s[0:1], 0x38
	s_load_dwordx4 s[56:59], s[0:1], 0x90
	v_writelane_b32 v253, s5, 15
	s_add_u32 s4, s54, 0xc5000
	v_writelane_b32 v253, s4, 16
	s_addc_u32 s4, s55, 0
	s_add_u32 s76, s54, 0x7300000
	s_addc_u32 s77, s55, 0
	s_add_u32 s78, s54, 0x9400000
	s_addc_u32 s79, s55, 0
	s_add_u32 s33, s54, 0xa500000
	v_writelane_b32 v253, s4, 17
	s_addc_u32 s4, s55, 0
	s_cmpk_lt_i32 s2, 0x220
	s_cselect_b64 s[8:9], -1, 0
	v_writelane_b32 v253, s8, 18
	s_add_u32 s51, s54, 0x2f00000
	s_addc_u32 s5, s55, 0
	v_writelane_b32 v253, s9, 19
	v_writelane_b32 v253, s5, 20
	s_waitcnt lgkmcnt(0)
	v_writelane_b32 v253, s6, 21
	s_cmp_lg_u64 s[6:7], 0
	s_load_dwordx2 s[0:1], s[0:1], 0xb0
	v_writelane_b32 v253, s7, 22
	s_cselect_b64 s[6:7], -1, 0
	v_writelane_b32 v253, s6, 23
	s_mov_b32 s73, 0
	v_mov_b32_e32 v1, 0
	v_writelane_b32 v253, s7, 24
	s_add_u32 s6, s54, 0xcc000
	s_addc_u32 s7, s55, 0
	v_writelane_b32 v253, s6, 25
	s_and_b32 s5, s2, 7
	v_mov_b32_e32 v177, 0xc3200000
	v_writelane_b32 v253, s7, 26
	v_writelane_b32 v253, s5, 27
	s_and_b32 s5, s2, 3
	s_cmp_lg_u32 s5, 0
	s_cselect_b64 s[6:7], -1, 0
	v_writelane_b32 v253, s6, 28
	v_mov_b32_e32 v207, 0x358637bd
	v_mov_b32_e32 v208, 0x260
	v_writelane_b32 v253, s7, 29
	s_add_u32 s6, s54, 0xc4020
	s_addc_u32 s7, s55, 0
	v_writelane_b32 v253, s6, 30
	s_add_u32 s5, s52, 0x1080000
	v_mov_b32_e32 v224, 1
	v_writelane_b32 v253, s7, 31
	v_writelane_b32 v253, s5, 32
	s_addc_u32 s5, s53, 0
	s_cmp_eq_u64 s[54:55], 0
	v_writelane_b32 v253, s5, 33
	s_cselect_b64 s[6:7], -1, 0
	v_writelane_b32 v253, s6, 34
	s_cmp_lg_u64 s[54:55], 0
	s_cselect_b64 s[94:95], -1, 0
	v_writelane_b32 v253, s7, 35
	s_add_u32 s5, s54, 0xc4024
	v_writelane_b32 v253, s5, 36
	s_addc_u32 s5, s55, 0
	v_writelane_b32 v253, s5, 37
	s_add_u32 s5, s52, 0x2100000
	v_writelane_b32 v253, s5, 38
	s_addc_u32 s5, s53, 0
	v_writelane_b32 v253, s5, 39
	s_add_u32 s5, s52, 0x2600000
	v_writelane_b32 v253, s5, 40
	s_addc_u32 s5, s53, 0
	s_add_u32 s6, s54, 0xc0200
	v_writelane_b32 v253, s5, 41
	s_addc_u32 s7, s55, 0
	v_writelane_b32 v253, s6, 42
	v_mov_b32_e32 v217, 0x4000
	v_mov_b32_e32 v218, 0xf149f2ca
	v_writelane_b32 v253, s7, 43
	s_add_u32 s6, s54, 0xc0400
	s_addc_u32 s7, s55, 0
	v_writelane_b32 v253, s6, 44
	v_mov_b64_e32 v[178:179], 0x100
	v_mov_b64_e32 v[180:181], 0xff
	v_writelane_b32 v253, s7, 45
	s_add_u32 s6, s54, 0xc0500
	s_addc_u32 s7, s55, 0
	v_writelane_b32 v253, s6, 46
	v_mov_b64_e32 v[182:183], 0x200
	v_mov_b64_e32 v[184:185], 0x1ff
	v_writelane_b32 v253, s7, 47
	s_add_u32 s6, s54, 0xc0600
	s_addc_u32 s7, s55, 0
	v_writelane_b32 v253, s6, 48
	v_mov_b32_e32 v219, 0x3e0293ee
	v_mov_b32_e32 v220, 0x3e38aa3b
	v_writelane_b32 v253, s7, 49
	s_add_u32 s6, s54, 0xc0700
	s_addc_u32 s7, s55, 0
	v_writelane_b32 v253, s6, 50
	v_mov_b32_e32 v211, 0x1143c00
	v_mov_b32_e32 v221, 0x1943c00
	v_writelane_b32 v253, s7, 51
	s_add_u32 s6, s54, 0xc0800
	s_addc_u32 s7, s55, 0
	v_writelane_b32 v253, s6, 52
	s_mov_b32 s50, 0x8000
	s_mov_b64 s[40:41], -1
	v_writelane_b32 v253, s7, 53
	s_add_u32 s6, s54, 0xc0900
	s_addc_u32 s7, s55, 0
	v_writelane_b32 v253, s6, 54
	s_mov_b64 s[90:91], 0x80
	s_mov_b32 s66, s73
	v_writelane_b32 v253, s7, 55
	s_add_u32 s6, s54, 0xc0a00
	s_addc_u32 s7, s55, 0
	v_writelane_b32 v253, s6, 56
	s_nop 1
	v_writelane_b32 v253, s7, 57
	s_add_u32 s6, s54, 0xc0b00
	s_addc_u32 s7, s55, 0
	v_writelane_b32 v253, s6, 58
	s_nop 1
	v_writelane_b32 v253, s7, 59
	s_add_u32 s6, s54, 0xc0c00
	s_addc_u32 s7, s55, 0
	v_writelane_b32 v253, s6, 60
	s_nop 1
	v_writelane_b32 v253, s7, 61
	s_add_u32 s6, s54, 0xc0d00
	s_addc_u32 s7, s55, 0
	v_writelane_b32 v253, s6, 62
	s_nop 1
	v_writelane_b32 v253, s7, 63
	s_add_u32 s6, s54, 0xc0e00
	s_addc_u32 s7, s55, 0
	v_writelane_b32 v254, s6, 0
	s_nop 1
	v_writelane_b32 v254, s7, 1
	s_add_u32 s6, s54, 0xc0f00
	s_addc_u32 s7, s55, 0
	v_writelane_b32 v254, s6, 2
	s_nop 1
	v_writelane_b32 v254, s7, 3
	s_add_u32 s6, s54, 0xc1000
	s_addc_u32 s7, s55, 0
	v_writelane_b32 v254, s6, 4
	s_nop 1
	v_writelane_b32 v254, s7, 5
	s_add_u32 s6, s54, 0xc1100
	s_addc_u32 s7, s55, 0
	v_writelane_b32 v254, s6, 6
	s_nop 1
	v_writelane_b32 v254, s7, 7
	s_add_u32 s6, s54, 0xc1200
	s_addc_u32 s7, s55, 0
	v_writelane_b32 v254, s6, 8
	s_nop 1
	v_writelane_b32 v254, s7, 9
	s_add_u32 s6, s54, 0xc1300
	s_addc_u32 s7, s55, 0
	v_writelane_b32 v254, s6, 10
	s_cmp_eq_u32 s60, 15
	s_nop 0
	v_writelane_b32 v254, s7, 11
	s_cselect_b64 s[6:7], -1, 0
	v_writelane_b32 v254, s6, 12
	s_cmp_eq_u32 s60, 14
	s_nop 0
	v_writelane_b32 v254, s7, 13
	s_cselect_b64 s[6:7], -1, 0
	v_writelane_b32 v254, s6, 14
	s_cmp_eq_u32 s60, 13
	s_nop 0
	v_writelane_b32 v254, s7, 15
	s_cselect_b64 s[6:7], -1, 0
	v_writelane_b32 v254, s6, 16
	s_cmp_eq_u32 s60, 12
	s_nop 0
	v_writelane_b32 v254, s7, 17
	s_cselect_b64 s[6:7], -1, 0
	v_writelane_b32 v254, s6, 18
	s_cmp_eq_u32 s60, 11
	s_nop 0
	v_writelane_b32 v254, s7, 19
	s_cselect_b64 s[6:7], -1, 0
	v_writelane_b32 v254, s6, 20
	s_cmp_eq_u32 s60, 10
	s_nop 0
	v_writelane_b32 v254, s7, 21
	s_cselect_b64 s[6:7], -1, 0
	v_writelane_b32 v254, s6, 22
	s_cmp_eq_u32 s60, 9
	s_nop 0
	v_writelane_b32 v254, s7, 23
	s_cselect_b64 s[6:7], -1, 0
	v_writelane_b32 v254, s6, 24
	s_cmp_eq_u32 s60, 8
	s_nop 0
	v_writelane_b32 v254, s7, 25
	s_cselect_b64 s[6:7], -1, 0
	v_writelane_b32 v254, s6, 26
	s_cmp_eq_u32 s60, 7
	s_nop 0
	v_writelane_b32 v254, s7, 27
	s_cselect_b64 s[6:7], -1, 0
	v_writelane_b32 v254, s6, 28
	s_cmp_eq_u32 s60, 6
	s_nop 0
	v_writelane_b32 v254, s7, 29
	s_cselect_b64 s[6:7], -1, 0
	v_writelane_b32 v254, s6, 30
	s_cmp_eq_u32 s60, 5
	s_nop 0
	v_writelane_b32 v254, s7, 31
	s_cselect_b64 s[6:7], -1, 0
	v_writelane_b32 v254, s6, 32
	s_cmp_eq_u32 s60, 4
	s_nop 0
	v_writelane_b32 v254, s7, 33
	s_cselect_b64 s[6:7], -1, 0
	v_writelane_b32 v254, s6, 34
	s_cmp_eq_u32 s60, 3
	s_nop 0
	v_writelane_b32 v254, s7, 35
	s_cselect_b64 s[6:7], -1, 0
	v_writelane_b32 v254, s6, 36
	s_cmp_eq_u32 s60, 2
	s_nop 0
	v_writelane_b32 v254, s7, 37
	s_cselect_b64 s[6:7], -1, 0
	v_writelane_b32 v254, s6, 38
	s_cmp_eq_u32 s60, 1
	s_nop 0
	v_writelane_b32 v254, s7, 39
	s_cselect_b64 s[6:7], -1, 0
	v_writelane_b32 v254, s6, 40
	s_cmp_eq_u32 s60, 0
	s_nop 0
	v_writelane_b32 v254, s7, 41
	s_cselect_b64 s[6:7], -1, 0
	s_lshl_b32 s5, s60, 8
	v_writelane_b32 v254, s6, 42
	s_add_u32 s5, s36, s5
	s_nop 0
	v_writelane_b32 v254, s7, 43
	s_addc_u32 s6, s37, 0
	s_add_u32 s8, s5, 0x1400
	s_addc_u32 s9, s6, 0
	v_writelane_b32 v254, s8, 44
	s_nop 1
	v_writelane_b32 v254, s9, 45
	s_add_u32 s8, s5, 0x2400
	s_addc_u32 s9, s6, 0
	v_writelane_b32 v254, s8, 46
	s_add_u32 s6, s54, 0xc3400
	s_addc_u32 s7, s55, 0
	v_writelane_b32 v254, s9, 47
	v_writelane_b32 v254, s6, 48
	s_nop 1
	v_writelane_b32 v254, s7, 49
	s_add_u32 s6, s54, 0xc3500
	s_addc_u32 s7, s55, 0
	v_writelane_b32 v254, s6, 50
	s_cmpk_lt_i32 s2, 0x100
	s_nop 0
	v_writelane_b32 v254, s7, 51
	s_cselect_b64 s[6:7], -1, 0
	v_writelane_b32 v254, s6, 52
	s_ashr_i32 s5, s2, 31
	s_nop 0
	v_writelane_b32 v254, s7, 53
	s_lshr_b32 s6, s5, 29
	s_add_i32 s6, s2, s6
	s_ashr_i32 s14, s6, 3
	s_and_b32 s6, s6, -8
	s_sub_i32 s12, s2, s6
	s_lshl_b32 s13, s12, 5
	s_ashr_i32 s6, s3, 31
	s_add_i32 s7, s3, s2
	s_add_u32 s8, s54, 0x9300000
	v_writelane_b32 v254, s8, 54
	s_addc_u32 s8, s55, 0
	s_cmpk_lt_i32 s2, 0x400
	v_writelane_b32 v254, s8, 55
	s_cselect_b64 s[8:9], -1, 0
	v_writelane_b32 v254, s8, 56
	s_lshl_b32 s15, s12, 7
	s_nop 0
	v_writelane_b32 v254, s9, 57
	s_add_u32 s8, s54, 0x5000000
	v_writelane_b32 v254, s8, 58
	s_addc_u32 s8, s55, 0
	v_writelane_b32 v254, s8, 59
	s_add_u32 s8, s54, 0xd200000
	v_writelane_b32 v254, s8, 60
	s_addc_u32 s8, s55, 0
	s_cmp_lt_i32 s86, 7
	v_writelane_b32 v254, s8, 61
	s_cselect_b64 s[8:9], -1, 0
	s_cmp_gt_i32 s87, 6
	s_cselect_b64 s[10:11], -1, 0
	s_and_b64 s[16:17], s[8:9], s[10:11]
	s_add_u32 s18, s54, 0x300000
	s_addc_u32 s19, s55, 0
	s_cmpk_lt_i32 s2, 0x200
	s_cselect_b64 s[8:9], -1, 0
	s_lshl_b32 s10, s12, 6
	v_writelane_b32 v254, s8, 62
	s_cmp_gt_u32 s87, 7
	v_writelane_b32 v255, s16, 0
	v_writelane_b32 v254, s9, 63
	s_cselect_b64 s[8:9], -1, 0
	v_writelane_b32 v255, s17, 1
	s_and_b64 s[8:9], s[16:17], s[8:9]
	v_writelane_b32 v255, s8, 2
	s_cmp_lt_i32 s12, 0
	s_nop 0
	v_writelane_b32 v255, s9, 3
	s_mul_i32 s8, s12, 33
	s_cselect_b32 s8, s8, s13
	s_mul_i32 s9, s12, 0x81
	s_mulk_i32 s12, 0x41
	s_cselect_b32 s9, s9, s15
	s_cselect_b32 s11, s12, s10
	s_add_i32 s8, s8, s14
	s_ashr_i32 s10, s8, 31
	s_lshr_b32 s10, s10, 27
	s_add_i32 s10, s8, s10
	s_and_b32 s12, s10, 0xffe0
	s_sub_i32 s8, s8, s12
	s_bfe_i32 s12, s8, 0x80000
	s_bfe_u32 s12, s12, 0x3000c
	s_add_i32 s12, s8, s12
	s_and_b32 s13, s12, 0xf8
	s_add_i32 s9, s9, s14
	s_sub_i32 s8, s8, s13
	s_ashr_i32 s13, s9, 31
	s_lshr_b32 s13, s13, 25
	s_add_i32 s13, s9, s13
	s_and_b32 s15, s13, 0xff80
	s_sub_i32 s9, s9, s15
	s_bfe_i32 s15, s9, 0x80000
	s_bfe_u32 s15, s15, 0x3000c
	s_add_i32 s15, s9, s15
	s_and_b32 s16, s15, 0xf8
	s_sub_i32 s9, s9, s16
	s_ashr_i32 s13, s13, 7
	s_sext_i32_i8 s9, s9
	s_lshl_b32 s16, s13, 11
	s_lshl_b32 s17, s9, 8
	s_ashr_i32 s10, s10, 5
	s_add_i32 s16, s16, s17
	s_lshl_b32 s10, s10, 3
	s_bfe_i32 s12, s12, 0x80000
	s_sext_i32_i8 s8, s8
	v_writelane_b32 v255, s16, 4
	s_sext_i32_i16 s12, s12
	s_add_i32 s16, s10, s8
	s_lshl_b32 s8, s13, 3
	s_bfe_i32 s10, s15, 0x80000
	s_add_i32 s20, s8, s9
	s_ashr_i32 s8, s12, 3
	s_sext_i32_i16 s10, s10
	v_writelane_b32 v255, s8, 5
	s_lshr_b32 s8, s12, 3
	s_ashr_i32 s17, s16, 31
	s_bfe_i64 s[8:9], s[8:9], 0x100000
	s_ashr_i32 s12, s10, 3
	v_writelane_b32 v255, s12, 6
	s_lshr_b32 s10, s10, 3
	s_lshl_b64 s[12:13], s[16:17], 21
	s_lshl_b64 s[22:23], s[8:9], 21
	s_add_u32 s12, s68, s12
	v_writelane_b32 v255, s22, 7
	s_addc_u32 s13, s69, s13
	s_nop 0
	v_writelane_b32 v255, s23, 8
	s_add_u32 s22, s12, 0x100000
	v_writelane_b32 v255, s12, 9
	s_addc_u32 s23, s13, 0
	s_add_i32 s11, s11, s14
	v_writelane_b32 v255, s13, 10
	s_ashr_i32 s12, s11, 31
	s_lshr_b32 s12, s12, 26
	s_add_i32 s12, s11, s12
	s_and_b32 s13, s12, 0xffc0
	s_sub_i32 s11, s11, s13
	s_bfe_i32 s13, s11, 0x80000
	s_bfe_u32 s13, s13, 0x3000c
	s_add_i32 s13, s11, s13
	s_and_b32 s14, s13, 0xf8
	s_sub_i32 s11, s11, s14
	s_ashr_i32 s12, s12, 6
	s_sext_i32_i8 s11, s11
	v_writelane_b32 v255, s22, 11
	s_lshl_b32 s14, s12, 11
	s_lshl_b32 s15, s11, 8
	v_writelane_b32 v255, s23, 12
	s_add_i32 s14, s14, s15
	v_writelane_b32 v255, s14, 13
	s_bfe_i32 s13, s13, 0x80000
	s_lshl_b64 s[8:9], s[8:9], 19
	s_sext_i32_i16 s13, s13
	v_writelane_b32 v255, s8, 14
	s_lshl_b32 s12, s12, 3
	s_add_i32 s14, s12, s11
	v_writelane_b32 v255, s9, 15
	s_ashr_i32 s8, s13, 3
	v_writelane_b32 v255, s8, 16
	s_mov_b32 s12, s16
	s_lshr_b32 s8, s13, 3
	v_writelane_b32 v255, s12, 17
	s_nop 1
	v_writelane_b32 v255, s13, 18
	s_lshl_b64 s[12:13], s[16:17], 19
	s_add_u32 s12, s76, s12
	s_addc_u32 s13, s77, s13
	s_add_u32 s16, s12, 0x40000
	v_writelane_b32 v255, s12, 19
	s_addc_u32 s17, s13, 0
	s_bfe_i64 s[10:11], s[10:11], 0x100000
	v_writelane_b32 v255, s13, 20
	v_writelane_b32 v255, s16, 21
	s_lshl_b64 s[10:11], s[10:11], 19
	s_ashr_i32 s21, s20, 31
	v_writelane_b32 v255, s17, 22
	v_writelane_b32 v255, s10, 23
	s_mov_b32 s16, 0x800000
	s_mov_b32 s17, 0x49800000
	v_writelane_b32 v255, s11, 24
	s_mov_b32 s10, s20
	v_writelane_b32 v255, s10, 25
	s_nop 1
	v_writelane_b32 v255, s11, 26
	s_lshl_b64 s[10:11], s[20:21], 19
	s_add_u32 s10, s64, s10
	s_addc_u32 s11, s65, s11
	s_add_u32 s12, s10, 0x40000
	v_writelane_b32 v255, s10, 27
	s_addc_u32 s13, s11, 0
	s_ashr_i32 s15, s14, 31
	v_writelane_b32 v255, s11, 28
	v_writelane_b32 v255, s12, 29
	s_mov_b32 s10, s14
	s_bfe_i64 s[8:9], s[8:9], 0x100000
	v_writelane_b32 v255, s13, 30
	v_writelane_b32 v255, s10, 31
	s_lshl_b64 s[8:9], s[8:9], 19
	s_nop 0
	v_writelane_b32 v255, s11, 32
	s_lshl_b64 s[10:11], s[14:15], 19
	s_add_u32 s8, s18, s8
	s_addc_u32 s9, s19, s9
	v_writelane_b32 v255, s18, 33
	s_add_u32 s12, s8, 0x40000
	v_writelane_b32 v255, s19, 34
	s_addc_u32 s13, s9, 0
	v_writelane_b32 v255, s12, 35
	s_add_u32 s10, s64, s10
	s_addc_u32 s11, s65, s11
	v_writelane_b32 v255, s13, 36
	s_add_u32 s12, s10, 0x40000
	v_writelane_b32 v255, s10, 37
	s_addc_u32 s13, s11, 0
	s_mov_b32 s14, 0xf149f2ca
	v_writelane_b32 v255, s11, 38
	v_writelane_b32 v255, s12, 39
	s_add_u32 s10, s8, 0x40080
	s_movk_i32 s15, 0x820
	v_writelane_b32 v255, s13, 40
	v_writelane_b32 v255, s8, 41
	s_addc_u32 s11, s9, 0
	s_mov_b32 s18, 0x650f000
	v_writelane_b32 v255, s9, 42
	s_abs_i32 s8, s3
	v_cvt_f32_u32_e32 v0, s8
	v_writelane_b32 v255, s10, 43
	s_sub_i32 s9, 0, s8
	v_rcp_iflag_f32_e32 v0, v0
	v_writelane_b32 v255, s11, 44
	s_waitcnt lgkmcnt(0)
	v_writelane_b32 v255, s0, 45
	s_movk_i32 s11, 0x78
	v_mul_f32_e32 v0, 0x4f7ffffe, v0
	v_cvt_u32_f32_e32 v0, v0
	v_writelane_b32 v255, s1, 46
	v_readfirstlane_b32 s10, v0
	s_mul_i32 s9, s9, s10
	s_mul_hi_u32 s9, s10, s9
	s_add_i32 s10, s10, s9
	s_abs_i32 s9, s7
	s_mul_hi_u32 s10, s9, s10
	s_mul_i32 s10, s10, s8
	s_sub_i32 s9, s9, s10
	s_ashr_i32 s7, s7, 31
	s_sub_i32 s10, s9, s8
	s_cmp_ge_u32 s9, s8
	s_cselect_b32 s9, s10, s9
	s_sub_i32 s10, s9, s8
	s_cmp_ge_u32 s9, s8
	s_cselect_b32 s8, s10, s9
	s_xor_b32 s8, s8, s7
	s_sub_i32 s7, s8, s7
	s_and_b32 s9, s7, 7
	s_lshl_b32 s9, s9, 5
	s_lshr_b32 s10, s7, 3
	s_or_b32 s9, s9, s10
	s_cmp_eq_u32 s3, 0x100
	s_cselect_b32 s7, s9, s7
	s_cmpk_lt_i32 s7, 0x100
	v_writelane_b32 v255, s7, 47
	s_cselect_b64 s[0:1], -1, 0
	v_writelane_b32 v255, s0, 48
	v_mbcnt_lo_u32_b32 v0, -1, 0
	v_mbcnt_hi_u32_b32 v205, -1, v0
	v_writelane_b32 v255, s1, 49
	s_add_i32 s0, 0, 0x20000
	v_writelane_b32 v255, s0, 50
	s_add_i32 s0, 0, 0xfffffee0
	v_writelane_b32 v255, s0, 51
	s_add_i32 s0, 0, 0xffffff20
	v_writelane_b32 v255, s0, 52
	s_add_i32 s0, 0, 0xffffff60
	v_writelane_b32 v255, s0, 53
	s_add_i32 s0, 0, 0xffffffa0
	v_writelane_b32 v255, s0, 54
	s_add_i32 s0, 0, 0x20004
	v_writelane_b32 v255, s0, 55
	s_mov_b64 s[0:1], 0
	v_writelane_b32 v255, s0, 56
	v_and_b32_e32 v0, 64, v205
	v_add_u32_e32 v206, 64, v0
	v_writelane_b32 v255, s1, 57
	v_xor_b32_e32 v216, 1, v205
	v_xor_b32_e32 v252, 2, v205
	v_xor_b32_e32 v239, 4, v205
	v_xor_b32_e32 v210, 16, v205
	v_xor_b32_e32 v209, 32, v205
	s_movk_i32 s7, 0x200
	s_lshl_b32 s8, s3, 5
	s_lshl_b32 s9, s3, 6
	s_add_i32 s10, 0, 0x20008
	v_writelane_b32 v255, s51, 58
	s_branch .LBB0_399
